# P8 epilogue: query scale applied with a per-unit scalar multiplier (C2 or 1.0) so the 8 v_cndmask per call are gone
# baseline (speedup 1.0000x reference)
.LBB0_1237:
	s_lshl_b32 s17, s24, 8
	s_ashr_i32 s19, s24, 2
	s_cmp_eq_u32 s19, 2
	v_lshl_add_u32 v150, s26, 8, v154
	s_cselect_b64 vcc, -1, 0
	s_cselect_b32 s64, s14, 1.0
	s_mov_b32 s65, s64
	s_cmpk_lt_u32 s17, 0x400
	v_lshlrev_b32_e32 v136, 3, v150
	s_cselect_b64 s[4:5], -1, 0
	v_and_b32_e32 v136, 0xfe78, v136
	s_or_b64 s[4:5], vcc, s[4:5]
	s_and_b64 s[24:25], s[6:7], s[4:5]
	v_lshlrev_b32_e32 v152, 2, v136
	s_and_saveexec_b64 s[4:5], s[24:25]
	s_cbranch_execz .LBB0_1239
	v_mov_b32_e32 v153, v137
	s_waitcnt vmcnt(0)
	v_mov_b64_e32 v[160:161], v[184:185]
	v_mov_b64_e32 v[162:163], v[186:187]
	v_mov_b64_e32 v[164:165], v[188:189]
	v_mov_b64_e32 v[166:167], v[190:191]
	v_pk_mul_f32 v[168:169], v[124:125], v[160:161]
	v_pk_mul_f32 v[170:171], v[124:125], v[164:165] op_sel:[1,0] op_sel_hi:[0,0]
	v_pk_mul_f32 v[176:177], v[120:121], v[166:167] op_sel:[1,0] op_sel_hi:[0,0]
	v_mov_b32_e32 v164, v161
	v_mul_f32_e32 v136, v127, v165
	v_mul_f32_e32 v172, v127, v161
	v_pk_mul_f32 v[174:175], v[120:121], v[162:163]
	v_mov_b32_e32 v166, v163
	v_mul_f32_e32 v178, v123, v167
	v_mul_f32_e32 v180, v123, v163
	v_pk_fma_f32 v[124:125], v[124:125], v[160:161], v[170:171] op_sel_hi:[1,0,1]
	v_mov_b32_e32 v160, v165
	v_pk_fma_f32 v[120:121], v[120:121], v[162:163], v[176:177] op_sel_hi:[1,0,1]
	v_mov_b32_e32 v162, v167
	v_pk_fma_f32 v[182:183], v[126:127], v[164:165], v[136:137] op_sel_hi:[1,1,0] neg_lo:[0,0,1] neg_hi:[0,0,1]
	v_pk_fma_f32 v[164:165], v[122:123], v[166:167], v[178:179] op_sel_hi:[1,1,0] neg_lo:[0,0,1] neg_hi:[0,0,1]
	v_pk_fma_f32 v[160:161], v[126:127], v[160:161], v[172:173] op_sel_hi:[1,1,0]
	v_pk_fma_f32 v[162:163], v[122:123], v[162:163], v[180:181] op_sel_hi:[1,1,0]
	v_sub_f32_e32 v120, v174, v176
	v_sub_f32_e32 v124, v168, v170
	v_mov_b32_e32 v122, v164
	v_mov_b32_e32 v126, v182
	v_mov_b32_e32 v123, v162
	v_mov_b32_e32 v127, v160
.LBB0_1239:
	s_or_b64 exec, exec, s[4:5]
	s_mul_hi_i32 s4, s19, 0x8100000
	s_mul_i32 s19, s19, 0x8100000
	s_and_b32 s5, s17, 0x300
	v_ashrrev_i32_e32 v151, 31, v150
	v_pk_mul_f32 v[162:163], v[124:125], s[64:65] op_sel_hi:[1,0]
	v_pk_mul_f32 v[168:169], v[122:123], s[64:65] op_sel_hi:[1,0]
	s_add_u32 s26, s86, s19
	v_lshlrev_b64 v[160:161], 11, v[150:151]
	v_pk_mul_f32 v[166:167], v[120:121], s[64:65] op_sel_hi:[1,0]
	v_or_b32_e32 v125, s5, v156
	s_addc_u32 s27, s87, s4
	v_pk_mul_f32 v[164:165], v[126:127], s[64:65] op_sel_hi:[1,0]
	v_lshl_add_u64 v[120:121], s[26:27], 0, v[160:161]
	v_lshlrev_b32_e32 v136, 1, v125
	v_lshl_add_u64 v[120:121], v[120:121], 0, v[136:137]
	v_cvt_pk_bf16_f32 v122, v162, v163
	v_cvt_pk_bf16_f32 v123, v164, v165
	v_cvt_pk_bf16_f32 v124, v166, v167
	v_cvt_pk_bf16_f32 v125, v168, v169
	global_store_dwordx4 v[120:121], v[122:125], off
	s_and_saveexec_b64 s[4:5], s[24:25]
	s_cbranch_execz .LBB0_1241
	v_mov_b32_e32 v153, v137
	v_mov_b64_e32 v[122:123], v[184:185]
	v_mov_b64_e32 v[124:125], v[186:187]
	v_mov_b64_e32 v[160:161], v[188:189]
	v_mov_b64_e32 v[162:163], v[190:191]
	v_pk_mul_f32 v[126:127], v[116:117], v[122:123]
	v_pk_mul_f32 v[152:153], v[116:117], v[160:161] op_sel:[1,0] op_sel_hi:[0,0]
	v_pk_mul_f32 v[170:171], v[112:113], v[162:163] op_sel:[1,0] op_sel_hi:[0,0]
	v_mov_b32_e32 v160, v123
	v_mul_f32_e32 v164, v119, v161
	v_mul_f32_e32 v166, v119, v123
	v_pk_mul_f32 v[168:169], v[112:113], v[124:125]
	v_mov_b32_e32 v162, v125
	v_mul_f32_e32 v172, v115, v163
	v_mul_f32_e32 v174, v115, v125
	v_pk_fma_f32 v[116:117], v[116:117], v[122:123], v[152:153] op_sel_hi:[1,0,1]
	v_mov_b32_e32 v122, v161
	v_pk_fma_f32 v[112:113], v[112:113], v[124:125], v[170:171] op_sel_hi:[1,0,1]
	v_mov_b32_e32 v124, v163
	v_pk_fma_f32 v[164:165], v[118:119], v[160:161], v[164:165] op_sel_hi:[1,1,0] neg_lo:[0,0,1] neg_hi:[0,0,1]
	v_pk_fma_f32 v[160:161], v[114:115], v[162:163], v[172:173] op_sel_hi:[1,1,0] neg_lo:[0,0,1] neg_hi:[0,0,1]
	v_pk_fma_f32 v[122:123], v[118:119], v[122:123], v[166:167] op_sel_hi:[1,1,0]
	v_pk_fma_f32 v[124:125], v[114:115], v[124:125], v[174:175] op_sel_hi:[1,1,0]
	v_sub_f32_e32 v112, v168, v170
	v_sub_f32_e32 v116, v126, v152
	v_mov_b32_e32 v114, v160
	v_mov_b32_e32 v118, v164
	v_mov_b32_e32 v115, v124
	v_mov_b32_e32 v119, v122
.LBB0_1241:
	s_or_b64 exec, exec, s[4:5]
	v_pk_mul_f32 v[122:123], v[116:117], s[64:65] op_sel_hi:[1,0]
	v_pk_mul_f32 v[124:125], v[118:119], s[64:65] op_sel_hi:[1,0]
	v_pk_mul_f32 v[126:127], v[112:113], s[64:65] op_sel_hi:[1,0]
	v_pk_mul_f32 v[152:153], v[114:115], s[64:65] op_sel_hi:[1,0]
	s_nop 0
	v_cvt_pk_bf16_f32 v112, v122, v123
	v_cvt_pk_bf16_f32 v113, v124, v125
	v_cvt_pk_bf16_f32 v114, v126, v127
	v_cvt_pk_bf16_f32 v115, v152, v153
	global_store_dwordx4 v[120:121], v[112:115], off offset:256
	s_nop 1
	v_or_b32_e32 v114, 16, v150
	v_lshlrev_b32_e32 v112, 3, v114
	v_and_b32_e32 v112, 0xfef8, v112
	v_lshlrev_b32_e32 v112, 2, v112
	s_and_saveexec_b64 s[4:5], s[24:25]
	s_cbranch_execz .LBB0_1243
	v_mov_b32_e32 v113, v137
	v_mov_b64_e32 v[116:117], v[192:193]
	v_mov_b64_e32 v[118:119], v[194:195]
	v_mov_b64_e32 v[120:121], v[196:197]
	v_mov_b64_e32 v[122:123], v[198:199]
	v_pk_mul_f32 v[124:125], v[108:109], v[116:117]
	v_pk_mul_f32 v[126:127], v[108:109], v[120:121] op_sel:[1,0] op_sel_hi:[0,0]
	v_pk_mul_f32 v[164:165], v[104:105], v[122:123] op_sel:[1,0] op_sel_hi:[0,0]
	v_mov_b32_e32 v120, v117
	v_mul_f32_e32 v152, v111, v121
	v_mul_f32_e32 v160, v111, v117
	v_pk_mul_f32 v[162:163], v[104:105], v[118:119]
	v_mov_b32_e32 v122, v119
	v_mul_f32_e32 v166, v107, v123
	v_mul_f32_e32 v168, v107, v119
	v_pk_fma_f32 v[108:109], v[108:109], v[116:117], v[126:127] op_sel_hi:[1,0,1]
	v_mov_b32_e32 v116, v121
	v_pk_fma_f32 v[104:105], v[104:105], v[118:119], v[164:165] op_sel_hi:[1,0,1]
	v_mov_b32_e32 v118, v123
	v_pk_fma_f32 v[152:153], v[110:111], v[120:121], v[152:153] op_sel_hi:[1,1,0] neg_lo:[0,0,1] neg_hi:[0,0,1]
	v_pk_fma_f32 v[120:121], v[106:107], v[122:123], v[166:167] op_sel_hi:[1,1,0] neg_lo:[0,0,1] neg_hi:[0,0,1]
	v_pk_fma_f32 v[116:117], v[110:111], v[116:117], v[160:161] op_sel_hi:[1,1,0]
	v_pk_fma_f32 v[118:119], v[106:107], v[118:119], v[168:169] op_sel_hi:[1,1,0]
	v_sub_f32_e32 v104, v162, v164
	v_sub_f32_e32 v108, v124, v126
	v_mov_b32_e32 v106, v120
	v_mov_b32_e32 v110, v152
	v_mov_b32_e32 v107, v118
	v_mov_b32_e32 v111, v116
.LBB0_1243:
	s_or_b64 exec, exec, s[4:5]
	v_ashrrev_i32_e32 v115, 31, v114
	v_lshlrev_b64 v[114:115], 11, v[114:115]
	v_pk_mul_f32 v[120:121], v[104:105], s[64:65] op_sel_hi:[1,0]
	v_pk_mul_f32 v[116:117], v[108:109], s[64:65] op_sel_hi:[1,0]
	v_pk_mul_f32 v[118:119], v[110:111], s[64:65] op_sel_hi:[1,0]
	v_pk_mul_f32 v[122:123], v[106:107], s[64:65] op_sel_hi:[1,0]
	v_lshl_add_u64 v[104:105], s[26:27], 0, v[114:115]
	v_lshl_add_u64 v[104:105], v[104:105], 0, v[136:137]
	v_cvt_pk_bf16_f32 v106, v116, v117
	v_cvt_pk_bf16_f32 v107, v118, v119
	v_cvt_pk_bf16_f32 v108, v120, v121
	v_cvt_pk_bf16_f32 v109, v122, v123
	global_store_dwordx4 v[104:105], v[106:109], off
	s_and_saveexec_b64 s[4:5], s[24:25]
	s_cbranch_execz .LBB0_1245
	v_mov_b32_e32 v113, v137
	v_mov_b64_e32 v[106:107], v[192:193]
	v_mov_b64_e32 v[108:109], v[194:195]
	v_mov_b64_e32 v[110:111], v[196:197]
	v_mov_b64_e32 v[112:113], v[198:199]
	v_pk_mul_f32 v[114:115], v[100:101], v[106:107]
	v_pk_mul_f32 v[116:117], v[100:101], v[110:111] op_sel:[1,0] op_sel_hi:[0,0]
	v_pk_mul_f32 v[124:125], v[96:97], v[112:113] op_sel:[1,0] op_sel_hi:[0,0]
	v_mov_b32_e32 v110, v107
	v_mul_f32_e32 v118, v103, v111
	v_mul_f32_e32 v120, v103, v107
	v_pk_mul_f32 v[122:123], v[96:97], v[108:109]
	v_mov_b32_e32 v112, v109
	v_mul_f32_e32 v126, v99, v113
	v_mul_f32_e32 v152, v99, v109
	v_pk_fma_f32 v[100:101], v[100:101], v[106:107], v[116:117] op_sel_hi:[1,0,1]
	v_mov_b32_e32 v106, v111
	v_pk_fma_f32 v[96:97], v[96:97], v[108:109], v[124:125] op_sel_hi:[1,0,1]
	v_mov_b32_e32 v108, v113
	v_pk_fma_f32 v[118:119], v[102:103], v[110:111], v[118:119] op_sel_hi:[1,1,0] neg_lo:[0,0,1] neg_hi:[0,0,1]
	v_pk_fma_f32 v[110:111], v[98:99], v[112:113], v[126:127] op_sel_hi:[1,1,0] neg_lo:[0,0,1] neg_hi:[0,0,1]
	v_pk_fma_f32 v[106:107], v[102:103], v[106:107], v[120:121] op_sel_hi:[1,1,0]
	v_pk_fma_f32 v[108:109], v[98:99], v[108:109], v[152:153] op_sel_hi:[1,1,0]
	v_sub_f32_e32 v96, v122, v124
	v_sub_f32_e32 v100, v114, v116
	v_mov_b32_e32 v98, v110
	v_mov_b32_e32 v102, v118
	v_mov_b32_e32 v99, v108
	v_mov_b32_e32 v103, v106
.LBB0_1245:
	s_or_b64 exec, exec, s[4:5]
	v_pk_mul_f32 v[106:107], v[100:101], s[64:65] op_sel_hi:[1,0]
	v_pk_mul_f32 v[108:109], v[102:103], s[64:65] op_sel_hi:[1,0]
	v_pk_mul_f32 v[110:111], v[96:97], s[64:65] op_sel_hi:[1,0]
	v_pk_mul_f32 v[112:113], v[98:99], s[64:65] op_sel_hi:[1,0]
	s_nop 0
	v_cvt_pk_bf16_f32 v96, v106, v107
	v_cvt_pk_bf16_f32 v97, v108, v109
	v_cvt_pk_bf16_f32 v98, v110, v111
	v_cvt_pk_bf16_f32 v99, v112, v113
	global_store_dwordx4 v[104:105], v[96:99], off offset:256
	s_nop 1
	v_or_b32_e32 v98, 32, v150
	v_lshlrev_b32_e32 v96, 3, v98
	v_and_b32_e32 v96, 0xff78, v96
	v_lshlrev_b32_e32 v96, 2, v96
	s_and_saveexec_b64 s[4:5], s[24:25]
	s_cbranch_execz .LBB0_1247
	v_mov_b32_e32 v97, v137
	v_mov_b64_e32 v[100:101], v[200:201]
	v_mov_b64_e32 v[102:103], v[202:203]
	v_mov_b64_e32 v[104:105], v[204:205]
	v_mov_b64_e32 v[106:107], v[206:207]
	v_pk_mul_f32 v[108:109], v[92:93], v[100:101]
	v_pk_mul_f32 v[110:111], v[92:93], v[104:105] op_sel:[1,0] op_sel_hi:[0,0]
	v_pk_mul_f32 v[118:119], v[88:89], v[106:107] op_sel:[1,0] op_sel_hi:[0,0]
	v_mov_b32_e32 v104, v101
	v_mul_f32_e32 v112, v95, v105
	v_mul_f32_e32 v114, v95, v101
	v_pk_mul_f32 v[116:117], v[88:89], v[102:103]
	v_mov_b32_e32 v106, v103
	v_mul_f32_e32 v120, v91, v107
	v_mul_f32_e32 v122, v91, v103
	v_pk_fma_f32 v[92:93], v[92:93], v[100:101], v[110:111] op_sel_hi:[1,0,1]
	v_mov_b32_e32 v100, v105
	v_pk_fma_f32 v[88:89], v[88:89], v[102:103], v[118:119] op_sel_hi:[1,0,1]
	v_mov_b32_e32 v102, v107
	v_pk_fma_f32 v[112:113], v[94:95], v[104:105], v[112:113] op_sel_hi:[1,1,0] neg_lo:[0,0,1] neg_hi:[0,0,1]
	v_pk_fma_f32 v[104:105], v[90:91], v[106:107], v[120:121] op_sel_hi:[1,1,0] neg_lo:[0,0,1] neg_hi:[0,0,1]
	v_pk_fma_f32 v[100:101], v[94:95], v[100:101], v[114:115] op_sel_hi:[1,1,0]
	v_pk_fma_f32 v[102:103], v[90:91], v[102:103], v[122:123] op_sel_hi:[1,1,0]
	v_sub_f32_e32 v88, v116, v118
	v_sub_f32_e32 v92, v108, v110
	v_mov_b32_e32 v90, v104
	v_mov_b32_e32 v94, v112
	v_mov_b32_e32 v91, v102
	v_mov_b32_e32 v95, v100
.LBB0_1247:
	s_or_b64 exec, exec, s[4:5]
	v_ashrrev_i32_e32 v99, 31, v98
	v_lshlrev_b64 v[98:99], 11, v[98:99]
	v_pk_mul_f32 v[104:105], v[88:89], s[64:65] op_sel_hi:[1,0]
	v_pk_mul_f32 v[100:101], v[92:93], s[64:65] op_sel_hi:[1,0]
	v_pk_mul_f32 v[102:103], v[94:95], s[64:65] op_sel_hi:[1,0]
	v_pk_mul_f32 v[106:107], v[90:91], s[64:65] op_sel_hi:[1,0]
	v_lshl_add_u64 v[88:89], s[26:27], 0, v[98:99]
	v_lshl_add_u64 v[88:89], v[88:89], 0, v[136:137]
	v_cvt_pk_bf16_f32 v90, v100, v101
	v_cvt_pk_bf16_f32 v91, v102, v103
	v_cvt_pk_bf16_f32 v92, v104, v105
	v_cvt_pk_bf16_f32 v93, v106, v107
	global_store_dwordx4 v[88:89], v[90:93], off
	s_and_saveexec_b64 s[4:5], s[24:25]
	s_cbranch_execz .LBB0_1249
	v_mov_b32_e32 v97, v137
	v_mov_b64_e32 v[90:91], v[200:201]
	v_mov_b64_e32 v[92:93], v[202:203]
	v_mov_b64_e32 v[94:95], v[204:205]
	v_mov_b64_e32 v[96:97], v[206:207]
	v_pk_mul_f32 v[98:99], v[84:85], v[90:91]
	v_pk_mul_f32 v[100:101], v[84:85], v[94:95] op_sel:[1,0] op_sel_hi:[0,0]
	v_pk_mul_f32 v[108:109], v[80:81], v[96:97] op_sel:[1,0] op_sel_hi:[0,0]
	v_mov_b32_e32 v94, v91
	v_mul_f32_e32 v102, v87, v95
	v_mul_f32_e32 v104, v87, v91
	v_pk_mul_f32 v[106:107], v[80:81], v[92:93]
	v_mov_b32_e32 v96, v93
	v_mul_f32_e32 v110, v83, v97
	v_mul_f32_e32 v112, v83, v93
	v_pk_fma_f32 v[84:85], v[84:85], v[90:91], v[100:101] op_sel_hi:[1,0,1]
	v_mov_b32_e32 v90, v95
	v_pk_fma_f32 v[80:81], v[80:81], v[92:93], v[108:109] op_sel_hi:[1,0,1]
	v_mov_b32_e32 v92, v97
	v_pk_fma_f32 v[102:103], v[86:87], v[94:95], v[102:103] op_sel_hi:[1,1,0] neg_lo:[0,0,1] neg_hi:[0,0,1]
	v_pk_fma_f32 v[94:95], v[82:83], v[96:97], v[110:111] op_sel_hi:[1,1,0] neg_lo:[0,0,1] neg_hi:[0,0,1]
	v_pk_fma_f32 v[90:91], v[86:87], v[90:91], v[104:105] op_sel_hi:[1,1,0]
	v_pk_fma_f32 v[92:93], v[82:83], v[92:93], v[112:113] op_sel_hi:[1,1,0]
	v_sub_f32_e32 v80, v106, v108
	v_sub_f32_e32 v84, v98, v100
	v_mov_b32_e32 v82, v94
	v_mov_b32_e32 v86, v102
	v_mov_b32_e32 v83, v92
	v_mov_b32_e32 v87, v90
.LBB0_1249:
	s_or_b64 exec, exec, s[4:5]
	v_pk_mul_f32 v[90:91], v[84:85], s[64:65] op_sel_hi:[1,0]
	v_pk_mul_f32 v[92:93], v[86:87], s[64:65] op_sel_hi:[1,0]
	v_pk_mul_f32 v[94:95], v[80:81], s[64:65] op_sel_hi:[1,0]
	v_pk_mul_f32 v[96:97], v[82:83], s[64:65] op_sel_hi:[1,0]
	s_nop 0
	v_cvt_pk_bf16_f32 v80, v90, v91
	v_cvt_pk_bf16_f32 v81, v92, v93
	v_cvt_pk_bf16_f32 v82, v94, v95
	v_cvt_pk_bf16_f32 v83, v96, v97
	global_store_dwordx4 v[88:89], v[80:83], off offset:256
	s_nop 1
	v_or_b32_e32 v82, 48, v150
	v_lshlrev_b32_e32 v80, 3, v82
	v_and_b32_e32 v80, 0xfff8, v80
	v_lshlrev_b32_e32 v80, 2, v80
	s_and_saveexec_b64 s[4:5], s[24:25]
	s_cbranch_execz .LBB0_1251
	v_mov_b32_e32 v81, v137
	v_mov_b64_e32 v[84:85], v[208:209]
	v_mov_b64_e32 v[86:87], v[210:211]
	v_mov_b64_e32 v[88:89], v[212:213]
	v_mov_b64_e32 v[90:91], v[214:215]
	v_pk_mul_f32 v[92:93], v[76:77], v[84:85]
	v_pk_mul_f32 v[94:95], v[76:77], v[88:89] op_sel:[1,0] op_sel_hi:[0,0]
	v_pk_mul_f32 v[102:103], v[72:73], v[90:91] op_sel:[1,0] op_sel_hi:[0,0]
	v_mov_b32_e32 v88, v85
	v_mul_f32_e32 v96, v79, v89
	v_mul_f32_e32 v98, v79, v85
	v_pk_mul_f32 v[100:101], v[72:73], v[86:87]
	v_mov_b32_e32 v90, v87
	v_mul_f32_e32 v104, v75, v91
	v_mul_f32_e32 v106, v75, v87
	v_pk_fma_f32 v[76:77], v[76:77], v[84:85], v[94:95] op_sel_hi:[1,0,1]
	v_mov_b32_e32 v84, v89
	v_pk_fma_f32 v[72:73], v[72:73], v[86:87], v[102:103] op_sel_hi:[1,0,1]
	v_mov_b32_e32 v86, v91
	v_pk_fma_f32 v[96:97], v[78:79], v[88:89], v[96:97] op_sel_hi:[1,1,0] neg_lo:[0,0,1] neg_hi:[0,0,1]
	v_pk_fma_f32 v[88:89], v[74:75], v[90:91], v[104:105] op_sel_hi:[1,1,0] neg_lo:[0,0,1] neg_hi:[0,0,1]
	v_pk_fma_f32 v[84:85], v[78:79], v[84:85], v[98:99] op_sel_hi:[1,1,0]
	v_pk_fma_f32 v[86:87], v[74:75], v[86:87], v[106:107] op_sel_hi:[1,1,0]
	v_sub_f32_e32 v72, v100, v102
	v_sub_f32_e32 v76, v92, v94
	v_mov_b32_e32 v74, v88
	v_mov_b32_e32 v78, v96
	v_mov_b32_e32 v75, v86
	v_mov_b32_e32 v79, v84
.LBB0_1251:
	s_or_b64 exec, exec, s[4:5]
	v_ashrrev_i32_e32 v83, 31, v82
	v_lshlrev_b64 v[82:83], 11, v[82:83]
	v_pk_mul_f32 v[88:89], v[72:73], s[64:65] op_sel_hi:[1,0]
	v_pk_mul_f32 v[84:85], v[76:77], s[64:65] op_sel_hi:[1,0]
	v_pk_mul_f32 v[86:87], v[78:79], s[64:65] op_sel_hi:[1,0]
	v_pk_mul_f32 v[90:91], v[74:75], s[64:65] op_sel_hi:[1,0]
	v_lshl_add_u64 v[72:73], s[26:27], 0, v[82:83]
	v_lshl_add_u64 v[72:73], v[72:73], 0, v[136:137]
	v_cvt_pk_bf16_f32 v74, v84, v85
	v_cvt_pk_bf16_f32 v75, v86, v87
	v_cvt_pk_bf16_f32 v76, v88, v89
	v_cvt_pk_bf16_f32 v77, v90, v91
	global_store_dwordx4 v[72:73], v[74:77], off
	s_and_saveexec_b64 s[4:5], s[24:25]
	s_cbranch_execz .LBB0_1253
	v_mov_b32_e32 v81, v137
	v_mov_b64_e32 v[74:75], v[208:209]
	v_mov_b64_e32 v[76:77], v[210:211]
	v_mov_b64_e32 v[78:79], v[212:213]
	v_mov_b64_e32 v[80:81], v[214:215]
	v_pk_mul_f32 v[82:83], v[68:69], v[74:75]
	v_pk_mul_f32 v[84:85], v[68:69], v[78:79] op_sel:[1,0] op_sel_hi:[0,0]
	v_pk_mul_f32 v[92:93], v[64:65], v[80:81] op_sel:[1,0] op_sel_hi:[0,0]
	v_mov_b32_e32 v78, v75
	v_mul_f32_e32 v86, v71, v79
	v_mul_f32_e32 v88, v71, v75
	v_pk_mul_f32 v[90:91], v[64:65], v[76:77]
	v_mov_b32_e32 v80, v77
	v_mul_f32_e32 v94, v67, v81
	v_mul_f32_e32 v96, v67, v77
	v_pk_fma_f32 v[68:69], v[68:69], v[74:75], v[84:85] op_sel_hi:[1,0,1]
	v_mov_b32_e32 v74, v79
	v_pk_fma_f32 v[64:65], v[64:65], v[76:77], v[92:93] op_sel_hi:[1,0,1]
	v_mov_b32_e32 v76, v81
	v_pk_fma_f32 v[86:87], v[70:71], v[78:79], v[86:87] op_sel_hi:[1,1,0] neg_lo:[0,0,1] neg_hi:[0,0,1]
	v_pk_fma_f32 v[78:79], v[66:67], v[80:81], v[94:95] op_sel_hi:[1,1,0] neg_lo:[0,0,1] neg_hi:[0,0,1]
	v_pk_fma_f32 v[74:75], v[70:71], v[74:75], v[88:89] op_sel_hi:[1,1,0]
	v_pk_fma_f32 v[76:77], v[66:67], v[76:77], v[96:97] op_sel_hi:[1,1,0]
	v_sub_f32_e32 v64, v90, v92
	v_sub_f32_e32 v68, v82, v84
	v_mov_b32_e32 v66, v78
	v_mov_b32_e32 v70, v86
	v_mov_b32_e32 v67, v76
	v_mov_b32_e32 v71, v74

.Lrope_skip2:
	v_pk_mul_f32 v[74:75], v[68:69], s[64:65] op_sel_hi:[1,0]
	v_pk_mul_f32 v[76:77], v[70:71], s[64:65] op_sel_hi:[1,0]
	v_pk_mul_f32 v[78:79], v[64:65], s[64:65] op_sel_hi:[1,0]
	v_pk_mul_f32 v[80:81], v[66:67], s[64:65] op_sel_hi:[1,0]
	s_nop 0
	v_cvt_pk_bf16_f32 v64, v74, v75
	v_cvt_pk_bf16_f32 v65, v76, v77
	v_cvt_pk_bf16_f32 v66, v78, v79
	v_cvt_pk_bf16_f32 v67, v80, v81
	global_store_dwordx4 v[72:73], v[64:67], off offset:256
	s_nop 1
	v_add_u32_e32 v66, 0x80, v150
	v_lshlrev_b32_e32 v64, 3, v66
	v_and_b32_e32 v64, 0xfe78, v64
	v_lshlrev_b32_e32 v64, 2, v64
	s_and_saveexec_b64 s[4:5], s[24:25]
	s_cbranch_execz .LBB0_1255
	v_mov_b32_e32 v65, v137
	s_waitcnt vmcnt(1)
	v_mov_b64_e32 v[68:69], v[184:185]
	v_mov_b64_e32 v[70:71], v[186:187]
	v_mov_b64_e32 v[72:73], v[188:189]
	v_mov_b64_e32 v[74:75], v[190:191]
	v_pk_mul_f32 v[76:77], v[60:61], v[68:69]
	v_pk_mul_f32 v[78:79], v[60:61], v[72:73] op_sel:[1,0] op_sel_hi:[0,0]
	v_pk_mul_f32 v[86:87], v[56:57], v[74:75] op_sel:[1,0] op_sel_hi:[0,0]
	v_mov_b32_e32 v72, v69
	v_mul_f32_e32 v80, v63, v73
	v_mul_f32_e32 v82, v63, v69
	v_pk_mul_f32 v[84:85], v[56:57], v[70:71]
	v_mov_b32_e32 v74, v71
	v_mul_f32_e32 v88, v59, v75
	v_mul_f32_e32 v90, v59, v71
	v_pk_fma_f32 v[60:61], v[60:61], v[68:69], v[78:79] op_sel_hi:[1,0,1]
	v_mov_b32_e32 v68, v73
	v_pk_fma_f32 v[56:57], v[56:57], v[70:71], v[86:87] op_sel_hi:[1,0,1]
	v_mov_b32_e32 v70, v75
	v_pk_fma_f32 v[80:81], v[62:63], v[72:73], v[80:81] op_sel_hi:[1,1,0] neg_lo:[0,0,1] neg_hi:[0,0,1]
	v_pk_fma_f32 v[72:73], v[58:59], v[74:75], v[88:89] op_sel_hi:[1,1,0] neg_lo:[0,0,1] neg_hi:[0,0,1]
	v_pk_fma_f32 v[68:69], v[62:63], v[68:69], v[82:83] op_sel_hi:[1,1,0]
	v_pk_fma_f32 v[70:71], v[58:59], v[70:71], v[90:91] op_sel_hi:[1,1,0]
	v_sub_f32_e32 v56, v84, v86
	v_sub_f32_e32 v60, v76, v78
	v_mov_b32_e32 v58, v72
	v_mov_b32_e32 v62, v80
	v_mov_b32_e32 v59, v70
	v_mov_b32_e32 v63, v68
.LBB0_1255:
	s_or_b64 exec, exec, s[4:5]
	v_ashrrev_i32_e32 v67, 31, v66
	v_lshlrev_b64 v[66:67], 11, v[66:67]
	v_pk_mul_f32 v[72:73], v[56:57], s[64:65] op_sel_hi:[1,0]
	v_pk_mul_f32 v[68:69], v[60:61], s[64:65] op_sel_hi:[1,0]
	v_pk_mul_f32 v[70:71], v[62:63], s[64:65] op_sel_hi:[1,0]
	v_pk_mul_f32 v[74:75], v[58:59], s[64:65] op_sel_hi:[1,0]
	v_lshl_add_u64 v[56:57], s[26:27], 0, v[66:67]
	v_lshl_add_u64 v[56:57], v[56:57], 0, v[136:137]
	v_cvt_pk_bf16_f32 v58, v68, v69
	v_cvt_pk_bf16_f32 v59, v70, v71
	v_cvt_pk_bf16_f32 v60, v72, v73
	v_cvt_pk_bf16_f32 v61, v74, v75
	global_store_dwordx4 v[56:57], v[58:61], off
	s_and_saveexec_b64 s[4:5], s[24:25]
	s_cbranch_execz .LBB0_1257
	v_mov_b32_e32 v65, v137
	v_mov_b64_e32 v[58:59], v[184:185]
	v_mov_b64_e32 v[60:61], v[186:187]
	v_mov_b64_e32 v[62:63], v[188:189]
	v_mov_b64_e32 v[64:65], v[190:191]
	v_pk_mul_f32 v[66:67], v[52:53], v[58:59]
	v_pk_mul_f32 v[68:69], v[52:53], v[62:63] op_sel:[1,0] op_sel_hi:[0,0]
	v_pk_mul_f32 v[76:77], v[48:49], v[64:65] op_sel:[1,0] op_sel_hi:[0,0]
	v_mov_b32_e32 v62, v59
	v_mul_f32_e32 v70, v55, v63
	v_mul_f32_e32 v72, v55, v59
	v_pk_mul_f32 v[74:75], v[48:49], v[60:61]
	v_mov_b32_e32 v64, v61
	v_mul_f32_e32 v78, v51, v65
	v_mul_f32_e32 v80, v51, v61
	v_pk_fma_f32 v[52:53], v[52:53], v[58:59], v[68:69] op_sel_hi:[1,0,1]
	v_mov_b32_e32 v58, v63
	v_pk_fma_f32 v[48:49], v[48:49], v[60:61], v[76:77] op_sel_hi:[1,0,1]
	v_mov_b32_e32 v60, v65
	v_pk_fma_f32 v[70:71], v[54:55], v[62:63], v[70:71] op_sel_hi:[1,1,0] neg_lo:[0,0,1] neg_hi:[0,0,1]
	v_pk_fma_f32 v[62:63], v[50:51], v[64:65], v[78:79] op_sel_hi:[1,1,0] neg_lo:[0,0,1] neg_hi:[0,0,1]
	v_pk_fma_f32 v[58:59], v[54:55], v[58:59], v[72:73] op_sel_hi:[1,1,0]
	v_pk_fma_f32 v[60:61], v[50:51], v[60:61], v[80:81] op_sel_hi:[1,1,0]
	v_sub_f32_e32 v48, v74, v76
	v_sub_f32_e32 v52, v66, v68
	v_mov_b32_e32 v50, v62
	v_mov_b32_e32 v54, v70
	v_mov_b32_e32 v51, v60
	v_mov_b32_e32 v55, v58
.LBB0_1257:
	s_or_b64 exec, exec, s[4:5]
	v_pk_mul_f32 v[58:59], v[52:53], s[64:65] op_sel_hi:[1,0]
	v_pk_mul_f32 v[60:61], v[54:55], s[64:65] op_sel_hi:[1,0]
	v_pk_mul_f32 v[62:63], v[48:49], s[64:65] op_sel_hi:[1,0]
	v_pk_mul_f32 v[64:65], v[50:51], s[64:65] op_sel_hi:[1,0]
	s_nop 0
	v_cvt_pk_bf16_f32 v48, v58, v59
	v_cvt_pk_bf16_f32 v49, v60, v61
	v_cvt_pk_bf16_f32 v50, v62, v63
	v_cvt_pk_bf16_f32 v51, v64, v65
	global_store_dwordx4 v[56:57], v[48:51], off offset:256
	s_nop 1
	v_add_u32_e32 v50, 0x90, v150
	v_lshlrev_b32_e32 v48, 3, v50
	v_and_b32_e32 v48, 0xfef8, v48
	v_lshlrev_b32_e32 v48, 2, v48
	s_and_saveexec_b64 s[4:5], s[24:25]
	s_cbranch_execz .LBB0_1259
	v_mov_b32_e32 v49, v137
	v_mov_b64_e32 v[52:53], v[192:193]
	v_mov_b64_e32 v[54:55], v[194:195]
	v_mov_b64_e32 v[56:57], v[196:197]
	v_mov_b64_e32 v[58:59], v[198:199]
	v_pk_mul_f32 v[60:61], v[44:45], v[52:53]
	v_pk_mul_f32 v[62:63], v[44:45], v[56:57] op_sel:[1,0] op_sel_hi:[0,0]
	v_pk_mul_f32 v[70:71], v[40:41], v[58:59] op_sel:[1,0] op_sel_hi:[0,0]
	v_mov_b32_e32 v56, v53
	v_mul_f32_e32 v64, v47, v57
	v_mul_f32_e32 v66, v47, v53
	v_pk_mul_f32 v[68:69], v[40:41], v[54:55]
	v_mov_b32_e32 v58, v55
	v_mul_f32_e32 v72, v43, v59
	v_mul_f32_e32 v74, v43, v55
	v_pk_fma_f32 v[44:45], v[44:45], v[52:53], v[62:63] op_sel_hi:[1,0,1]
	v_mov_b32_e32 v52, v57
	v_pk_fma_f32 v[40:41], v[40:41], v[54:55], v[70:71] op_sel_hi:[1,0,1]
	v_mov_b32_e32 v54, v59
	v_pk_fma_f32 v[64:65], v[46:47], v[56:57], v[64:65] op_sel_hi:[1,1,0] neg_lo:[0,0,1] neg_hi:[0,0,1]
	v_pk_fma_f32 v[56:57], v[42:43], v[58:59], v[72:73] op_sel_hi:[1,1,0] neg_lo:[0,0,1] neg_hi:[0,0,1]
	v_pk_fma_f32 v[52:53], v[46:47], v[52:53], v[66:67] op_sel_hi:[1,1,0]
	v_pk_fma_f32 v[54:55], v[42:43], v[54:55], v[74:75] op_sel_hi:[1,1,0]
	v_sub_f32_e32 v40, v68, v70
	v_sub_f32_e32 v44, v60, v62
	v_mov_b32_e32 v42, v56
	v_mov_b32_e32 v46, v64
	v_mov_b32_e32 v43, v54
	v_mov_b32_e32 v47, v52
.LBB0_1259:
	s_or_b64 exec, exec, s[4:5]
	v_ashrrev_i32_e32 v51, 31, v50
	v_lshlrev_b64 v[50:51], 11, v[50:51]
	v_pk_mul_f32 v[56:57], v[40:41], s[64:65] op_sel_hi:[1,0]
	v_pk_mul_f32 v[52:53], v[44:45], s[64:65] op_sel_hi:[1,0]
	v_pk_mul_f32 v[54:55], v[46:47], s[64:65] op_sel_hi:[1,0]
	v_pk_mul_f32 v[58:59], v[42:43], s[64:65] op_sel_hi:[1,0]
	v_lshl_add_u64 v[40:41], s[26:27], 0, v[50:51]
	v_lshl_add_u64 v[40:41], v[40:41], 0, v[136:137]
	v_cvt_pk_bf16_f32 v42, v52, v53
	v_cvt_pk_bf16_f32 v43, v54, v55
	v_cvt_pk_bf16_f32 v44, v56, v57
	v_cvt_pk_bf16_f32 v45, v58, v59
	global_store_dwordx4 v[40:41], v[42:45], off
	s_and_saveexec_b64 s[4:5], s[24:25]
	s_cbranch_execz .LBB0_1261
	v_mov_b32_e32 v49, v137
	v_mov_b64_e32 v[42:43], v[192:193]
	v_mov_b64_e32 v[44:45], v[194:195]
	v_mov_b64_e32 v[46:47], v[196:197]
	v_mov_b64_e32 v[48:49], v[198:199]
	v_pk_mul_f32 v[50:51], v[36:37], v[42:43]
	v_pk_mul_f32 v[52:53], v[36:37], v[46:47] op_sel:[1,0] op_sel_hi:[0,0]
	v_pk_mul_f32 v[60:61], v[32:33], v[48:49] op_sel:[1,0] op_sel_hi:[0,0]
	v_mov_b32_e32 v46, v43
	v_mul_f32_e32 v54, v39, v47
	v_mul_f32_e32 v56, v39, v43
	v_pk_mul_f32 v[58:59], v[32:33], v[44:45]
	v_mov_b32_e32 v48, v45
	v_mul_f32_e32 v62, v35, v49
	v_mul_f32_e32 v64, v35, v45
	v_pk_fma_f32 v[36:37], v[36:37], v[42:43], v[52:53] op_sel_hi:[1,0,1]
	v_mov_b32_e32 v42, v47
	v_pk_fma_f32 v[32:33], v[32:33], v[44:45], v[60:61] op_sel_hi:[1,0,1]
	v_mov_b32_e32 v44, v49
	v_pk_fma_f32 v[54:55], v[38:39], v[46:47], v[54:55] op_sel_hi:[1,1,0] neg_lo:[0,0,1] neg_hi:[0,0,1]
	v_pk_fma_f32 v[46:47], v[34:35], v[48:49], v[62:63] op_sel_hi:[1,1,0] neg_lo:[0,0,1] neg_hi:[0,0,1]
	v_pk_fma_f32 v[42:43], v[38:39], v[42:43], v[56:57] op_sel_hi:[1,1,0]
	v_pk_fma_f32 v[44:45], v[34:35], v[44:45], v[64:65] op_sel_hi:[1,1,0]
	v_sub_f32_e32 v32, v58, v60
	v_sub_f32_e32 v36, v50, v52
	v_mov_b32_e32 v34, v46
	v_mov_b32_e32 v38, v54
	v_mov_b32_e32 v35, v44
	v_mov_b32_e32 v39, v42
.LBB0_1261:
	s_or_b64 exec, exec, s[4:5]
	v_pk_mul_f32 v[42:43], v[36:37], s[64:65] op_sel_hi:[1,0]
	v_pk_mul_f32 v[44:45], v[38:39], s[64:65] op_sel_hi:[1,0]
	v_pk_mul_f32 v[46:47], v[32:33], s[64:65] op_sel_hi:[1,0]
	v_pk_mul_f32 v[48:49], v[34:35], s[64:65] op_sel_hi:[1,0]
	s_nop 0
	v_cvt_pk_bf16_f32 v32, v42, v43
	v_cvt_pk_bf16_f32 v33, v44, v45
	v_cvt_pk_bf16_f32 v34, v46, v47
	v_cvt_pk_bf16_f32 v35, v48, v49
	global_store_dwordx4 v[40:41], v[32:35], off offset:256
	s_nop 1
	v_add_u32_e32 v34, 0xa0, v150
	v_lshlrev_b32_e32 v32, 3, v34
	v_and_b32_e32 v32, 0xff78, v32
	v_lshlrev_b32_e32 v32, 2, v32
	s_and_saveexec_b64 s[4:5], s[24:25]
	s_cbranch_execz .LBB0_1263
	v_mov_b32_e32 v33, v137
	v_mov_b64_e32 v[36:37], v[200:201]
	v_mov_b64_e32 v[38:39], v[202:203]
	v_mov_b64_e32 v[40:41], v[204:205]
	v_mov_b64_e32 v[42:43], v[206:207]
	v_pk_mul_f32 v[44:45], v[28:29], v[36:37]
	v_pk_mul_f32 v[46:47], v[28:29], v[40:41] op_sel:[1,0] op_sel_hi:[0,0]
	v_pk_mul_f32 v[54:55], v[24:25], v[42:43] op_sel:[1,0] op_sel_hi:[0,0]
	v_mov_b32_e32 v40, v37
	v_mul_f32_e32 v48, v31, v41
	v_mul_f32_e32 v50, v31, v37
	v_pk_mul_f32 v[52:53], v[24:25], v[38:39]
	v_mov_b32_e32 v42, v39
	v_mul_f32_e32 v56, v27, v43
	v_mul_f32_e32 v58, v27, v39
	v_pk_fma_f32 v[28:29], v[28:29], v[36:37], v[46:47] op_sel_hi:[1,0,1]
	v_mov_b32_e32 v36, v41
	v_pk_fma_f32 v[24:25], v[24:25], v[38:39], v[54:55] op_sel_hi:[1,0,1]
	v_mov_b32_e32 v38, v43
	v_pk_fma_f32 v[48:49], v[30:31], v[40:41], v[48:49] op_sel_hi:[1,1,0] neg_lo:[0,0,1] neg_hi:[0,0,1]
	v_pk_fma_f32 v[40:41], v[26:27], v[42:43], v[56:57] op_sel_hi:[1,1,0] neg_lo:[0,0,1] neg_hi:[0,0,1]
	v_pk_fma_f32 v[36:37], v[30:31], v[36:37], v[50:51] op_sel_hi:[1,1,0]
	v_pk_fma_f32 v[38:39], v[26:27], v[38:39], v[58:59] op_sel_hi:[1,1,0]
	v_sub_f32_e32 v24, v52, v54
	v_sub_f32_e32 v28, v44, v46
	v_mov_b32_e32 v26, v40
	v_mov_b32_e32 v30, v48
	v_mov_b32_e32 v27, v38
	v_mov_b32_e32 v31, v36
.LBB0_1263:
	s_or_b64 exec, exec, s[4:5]
	v_ashrrev_i32_e32 v35, 31, v34
	v_lshlrev_b64 v[34:35], 11, v[34:35]
	v_pk_mul_f32 v[40:41], v[24:25], s[64:65] op_sel_hi:[1,0]
	v_pk_mul_f32 v[36:37], v[28:29], s[64:65] op_sel_hi:[1,0]
	v_pk_mul_f32 v[38:39], v[30:31], s[64:65] op_sel_hi:[1,0]
	v_pk_mul_f32 v[42:43], v[26:27], s[64:65] op_sel_hi:[1,0]
	v_lshl_add_u64 v[24:25], s[26:27], 0, v[34:35]
	v_lshl_add_u64 v[24:25], v[24:25], 0, v[136:137]
	v_cvt_pk_bf16_f32 v26, v36, v37
	v_cvt_pk_bf16_f32 v27, v38, v39
	v_cvt_pk_bf16_f32 v28, v40, v41
	v_cvt_pk_bf16_f32 v29, v42, v43
	global_store_dwordx4 v[24:25], v[26:29], off
	s_and_saveexec_b64 s[4:5], s[24:25]
	s_cbranch_execz .LBB0_1265
	v_mov_b32_e32 v33, v137
	v_mov_b64_e32 v[26:27], v[200:201]
	v_mov_b64_e32 v[28:29], v[202:203]
	v_mov_b64_e32 v[30:31], v[204:205]
	v_mov_b64_e32 v[32:33], v[206:207]
	v_pk_mul_f32 v[34:35], v[20:21], v[26:27]
	v_pk_mul_f32 v[36:37], v[20:21], v[30:31] op_sel:[1,0] op_sel_hi:[0,0]
	v_pk_mul_f32 v[44:45], v[16:17], v[32:33] op_sel:[1,0] op_sel_hi:[0,0]
	v_mov_b32_e32 v30, v27
	v_mul_f32_e32 v38, v23, v31
	v_mul_f32_e32 v40, v23, v27
	v_pk_mul_f32 v[42:43], v[16:17], v[28:29]
	v_mov_b32_e32 v32, v29
	v_mul_f32_e32 v46, v19, v33
	v_mul_f32_e32 v48, v19, v29
	v_pk_fma_f32 v[20:21], v[20:21], v[26:27], v[36:37] op_sel_hi:[1,0,1]
	v_mov_b32_e32 v26, v31
	v_pk_fma_f32 v[16:17], v[16:17], v[28:29], v[44:45] op_sel_hi:[1,0,1]
	v_mov_b32_e32 v28, v33
	v_pk_fma_f32 v[38:39], v[22:23], v[30:31], v[38:39] op_sel_hi:[1,1,0] neg_lo:[0,0,1] neg_hi:[0,0,1]
	v_pk_fma_f32 v[30:31], v[18:19], v[32:33], v[46:47] op_sel_hi:[1,1,0] neg_lo:[0,0,1] neg_hi:[0,0,1]
	v_pk_fma_f32 v[26:27], v[22:23], v[26:27], v[40:41] op_sel_hi:[1,1,0]
	v_pk_fma_f32 v[28:29], v[18:19], v[28:29], v[48:49] op_sel_hi:[1,1,0]
	v_sub_f32_e32 v16, v42, v44
	v_sub_f32_e32 v20, v34, v36
	v_mov_b32_e32 v18, v30
	v_mov_b32_e32 v22, v38
	v_mov_b32_e32 v19, v28
	v_mov_b32_e32 v23, v26
.LBB0_1265:
	s_or_b64 exec, exec, s[4:5]
	v_pk_mul_f32 v[26:27], v[20:21], s[64:65] op_sel_hi:[1,0]
	v_pk_mul_f32 v[28:29], v[22:23], s[64:65] op_sel_hi:[1,0]
	v_pk_mul_f32 v[30:31], v[16:17], s[64:65] op_sel_hi:[1,0]
	v_pk_mul_f32 v[32:33], v[18:19], s[64:65] op_sel_hi:[1,0]
	s_nop 0
	v_cvt_pk_bf16_f32 v16, v26, v27
	v_cvt_pk_bf16_f32 v17, v28, v29
	v_cvt_pk_bf16_f32 v18, v30, v31
	v_cvt_pk_bf16_f32 v19, v32, v33
	global_store_dwordx4 v[24:25], v[16:19], off offset:256
	s_nop 1
	v_add_u32_e32 v18, 0xb0, v150
	v_lshlrev_b32_e32 v16, 3, v18
	v_and_b32_e32 v16, 0xfff8, v16
	v_lshlrev_b32_e32 v16, 2, v16
	s_and_saveexec_b64 s[4:5], s[24:25]
	s_cbranch_execz .LBB0_1267
	v_mov_b32_e32 v17, v137
	v_mov_b64_e32 v[20:21], v[208:209]
	v_mov_b64_e32 v[22:23], v[210:211]
	v_mov_b64_e32 v[24:25], v[212:213]
	v_mov_b64_e32 v[26:27], v[214:215]
	v_pk_mul_f32 v[28:29], v[12:13], v[20:21]
	v_pk_mul_f32 v[30:31], v[12:13], v[24:25] op_sel:[1,0] op_sel_hi:[0,0]
	v_pk_mul_f32 v[38:39], v[8:9], v[26:27] op_sel:[1,0] op_sel_hi:[0,0]
	v_mov_b32_e32 v24, v21
	v_mul_f32_e32 v32, v15, v25
	v_mul_f32_e32 v34, v15, v21
	v_pk_mul_f32 v[36:37], v[8:9], v[22:23]
	v_mov_b32_e32 v26, v23
	v_mul_f32_e32 v40, v11, v27
	v_mul_f32_e32 v42, v11, v23
	v_pk_fma_f32 v[12:13], v[12:13], v[20:21], v[30:31] op_sel_hi:[1,0,1]
	v_mov_b32_e32 v20, v25
	v_pk_fma_f32 v[8:9], v[8:9], v[22:23], v[38:39] op_sel_hi:[1,0,1]
	v_mov_b32_e32 v22, v27
	v_pk_fma_f32 v[32:33], v[14:15], v[24:25], v[32:33] op_sel_hi:[1,1,0] neg_lo:[0,0,1] neg_hi:[0,0,1]
	v_pk_fma_f32 v[24:25], v[10:11], v[26:27], v[40:41] op_sel_hi:[1,1,0] neg_lo:[0,0,1] neg_hi:[0,0,1]
	v_pk_fma_f32 v[20:21], v[14:15], v[20:21], v[34:35] op_sel_hi:[1,1,0]
	v_pk_fma_f32 v[22:23], v[10:11], v[22:23], v[42:43] op_sel_hi:[1,1,0]
	v_sub_f32_e32 v8, v36, v38
	v_sub_f32_e32 v12, v28, v30
	v_mov_b32_e32 v10, v24
	v_mov_b32_e32 v14, v32
	v_mov_b32_e32 v11, v22
	v_mov_b32_e32 v15, v20
.LBB0_1267:
	s_or_b64 exec, exec, s[4:5]
	v_ashrrev_i32_e32 v19, 31, v18
	v_lshlrev_b64 v[18:19], 11, v[18:19]
	v_pk_mul_f32 v[24:25], v[8:9], s[64:65] op_sel_hi:[1,0]
	v_pk_mul_f32 v[20:21], v[12:13], s[64:65] op_sel_hi:[1,0]
	v_pk_mul_f32 v[22:23], v[14:15], s[64:65] op_sel_hi:[1,0]
	v_pk_mul_f32 v[26:27], v[10:11], s[64:65] op_sel_hi:[1,0]
	v_lshl_add_u64 v[8:9], s[26:27], 0, v[18:19]
	v_lshl_add_u64 v[8:9], v[8:9], 0, v[136:137]
	v_cvt_pk_bf16_f32 v10, v20, v21
	v_cvt_pk_bf16_f32 v11, v22, v23
	v_cvt_pk_bf16_f32 v12, v24, v25
	v_cvt_pk_bf16_f32 v13, v26, v27
	global_store_dwordx4 v[8:9], v[10:13], off
	s_and_saveexec_b64 s[4:5], s[24:25]
	s_cbranch_execz .LBB0_1269
	v_mov_b32_e32 v17, v137
	v_mov_b64_e32 v[10:11], v[208:209]
	v_mov_b64_e32 v[12:13], v[210:211]
	v_mov_b64_e32 v[14:15], v[212:213]
	v_mov_b64_e32 v[16:17], v[214:215]
	v_pk_mul_f32 v[18:19], v[4:5], v[10:11]
	v_pk_mul_f32 v[20:21], v[4:5], v[14:15] op_sel:[1,0] op_sel_hi:[0,0]
	v_pk_mul_f32 v[28:29], v[0:1], v[16:17] op_sel:[1,0] op_sel_hi:[0,0]
	v_mov_b32_e32 v14, v11
	v_mul_f32_e32 v22, v7, v15
	v_mul_f32_e32 v24, v7, v11
	v_pk_mul_f32 v[26:27], v[0:1], v[12:13]
	v_mov_b32_e32 v16, v13
	v_mul_f32_e32 v30, v3, v17
	v_mul_f32_e32 v32, v3, v13
	v_pk_fma_f32 v[4:5], v[4:5], v[10:11], v[20:21] op_sel_hi:[1,0,1]
	v_mov_b32_e32 v10, v15
	v_pk_fma_f32 v[0:1], v[0:1], v[12:13], v[28:29] op_sel_hi:[1,0,1]
	v_mov_b32_e32 v12, v17
	v_pk_fma_f32 v[22:23], v[6:7], v[14:15], v[22:23] op_sel_hi:[1,1,0] neg_lo:[0,0,1] neg_hi:[0,0,1]
	v_pk_fma_f32 v[14:15], v[2:3], v[16:17], v[30:31] op_sel_hi:[1,1,0] neg_lo:[0,0,1] neg_hi:[0,0,1]
	v_pk_fma_f32 v[10:11], v[6:7], v[10:11], v[24:25] op_sel_hi:[1,1,0]
	v_pk_fma_f32 v[12:13], v[2:3], v[12:13], v[32:33] op_sel_hi:[1,1,0]
	v_sub_f32_e32 v0, v26, v28
	v_sub_f32_e32 v4, v18, v20
	v_mov_b32_e32 v2, v14
	v_mov_b32_e32 v6, v22
	v_mov_b32_e32 v3, v12
	v_mov_b32_e32 v7, v10
.LBB0_1269:
	s_or_b64 exec, exec, s[4:5]
	v_pk_mul_f32 v[10:11], v[4:5], s[64:65] op_sel_hi:[1,0]
	v_pk_mul_f32 v[12:13], v[6:7], s[64:65] op_sel_hi:[1,0]
	v_pk_mul_f32 v[14:15], v[0:1], s[64:65] op_sel_hi:[1,0]
	v_pk_mul_f32 v[16:17], v[2:3], s[64:65] op_sel_hi:[1,0]
	s_mov_b64 s[4:5], -1
	s_andn2_b64 vcc, exec, s[8:9]
	v_cvt_pk_bf16_f32 v0, v10, v11
	v_cvt_pk_bf16_f32 v1, v12, v13
	v_cvt_pk_bf16_f32 v2, v14, v15
	v_cvt_pk_bf16_f32 v3, v16, v17
	global_store_dwordx4 v[8:9], v[0:3], off offset:256
	s_cbranch_vccnz .LBB0_1226
	s_andn2_b64 vcc, exec, s[0:1]
	s_cbranch_vccnz .LBB0_1225
	s_barrier
	s_branch .LBB0_1225
